# scan1 tail: next chunk dequeue issued behind the last stores so its round trip overlaps the drain
# speedup vs baseline: 1.0006x; 1.0006x over previous
.LBB0_468:
	s_add_u32 s4, s24, 0x74100
	s_addc_u32 s5, s25, 0
	s_add_u32 s3, s24, 0x6c000
	s_addc_u32 s16, s25, 0
	s_add_u32 s14, s24, 0x3400000
	s_addc_u32 s15, s25, 0
	s_add_i32 s17, 0, 0x20080
	s_mov_b32 s43, 0
	v_mov_b32_e32 v41, 0
	s_movk_i32 s27, 0x407f
	s_mov_b32 s28, 0xfe03f81
	s_mov_b32 s29, 0x1fc07f
	v_mov_b32_e32 v44, s17
	s_and_saveexec_b64 s[98:99], s[92:93]
	s_cbranch_execz .Lpfd_s1_skip
	v_mov_b32_e32 v253, 1
	global_atomic_add v253, v41, v253, s[4:5] sc0
.Lpfd_s1_skip:
	s_mov_b64 exec, s[98:99]
	s_mov_b32 s99, 0
	s_branch .LBB0_472

.LBB0_472:
	s_barrier
	s_and_saveexec_b64 s[0:1], s[92:93]
	s_cbranch_execz .LBB0_506
	s_mov_b64 s[38:39], exec
	v_mbcnt_lo_u32_b32 v0, s38, 0
	v_mbcnt_hi_u32_b32 v0, s39, v0
	v_cmp_eq_u32_e32 vcc, 0, v0
	s_and_saveexec_b64 s[36:37], vcc
	s_cbranch_execz .LBB0_475
	s_bcnt1_i32_b64 s8, s[38:39]
	v_mov_b32_e32 v1, s8
	s_waitcnt vmcnt(0)
	v_mov_b32_e32 v1, v253

.LBB0_517:
	v_add_u32_e32 v13, s18, v12
	ds_read_b128 v[18:21], v13
	ds_read_b128 v[22:25], v13 offset:16
	ds_read_b128 v[26:29], v13 offset:32
	ds_read_b128 v[30:33], v13 offset:48
	ds_read_b128 v[34:37], v13 offset:2048
	ds_read_b128 v[46:49], v13 offset:2064
	ds_read_b128 v[50:53], v13 offset:2080
	ds_read_b128 v[54:57], v13 offset:2096
	ds_read_b128 v[58:61], v13 offset:4096
	ds_read_b128 v[62:65], v13 offset:4112
	ds_read_b128 v[66:69], v13 offset:4128
	ds_read_b128 v[70:73], v13 offset:4144
	ds_read_b128 v[74:77], v13 offset:6144
	ds_read_b128 v[78:81], v13 offset:6160
	ds_read_b128 v[82:85], v13 offset:6176
	ds_read_b128 v[86:89], v13 offset:6192
	s_waitcnt lgkmcnt(14)
	v_mov_b32_e32 v38, v18
	v_mov_b32_e32 v39, v20
	v_mov_b32_e32 v20, v19
	v_mov_b32_e32 v18, v22
	v_mov_b32_e32 v19, v24
	v_mov_b32_e32 v24, v23
	s_waitcnt lgkmcnt(13)
	v_mov_b32_e32 v22, v26
	v_mov_b32_e32 v23, v28
	v_mov_b32_e32 v28, v27
	s_waitcnt lgkmcnt(12)
	v_mov_b32_e32 v26, v30
	v_mov_b32_e32 v27, v32
	v_mov_b32_e32 v32, v31
	s_waitcnt lgkmcnt(11)
	v_mov_b32_e32 v30, v34
	v_mov_b32_e32 v31, v36
	v_mov_b32_e32 v36, v35
	s_waitcnt lgkmcnt(10)
	v_mov_b32_e32 v34, v46
	v_mov_b32_e32 v35, v48
	v_mov_b32_e32 v48, v47
	s_waitcnt lgkmcnt(9)
	v_mov_b32_e32 v42, v50
	v_mov_b32_e32 v43, v52
	v_mov_b32_e32 v52, v51
	s_waitcnt lgkmcnt(8)
	v_mov_b32_e32 v46, v54
	v_mov_b32_e32 v47, v56
	v_mov_b32_e32 v56, v55
	v_pk_fma_f32 v[14:15], v[38:39], v[14:15], v[20:21]
	v_pk_mul_f32 v[8:9], v[8:9], v[38:39]
	v_pk_fma_f32 v[10:11], v[18:19], v[10:11], v[24:25]
	v_pk_mul_f32 v[4:5], v[4:5], v[18:19]
	v_pk_fma_f32 v[6:7], v[22:23], v[6:7], v[28:29]
	v_pk_mul_f32 v[0:1], v[0:1], v[22:23]
	v_pk_fma_f32 v[2:3], v[26:27], v[2:3], v[32:33]
	v_pk_mul_f32 v[16:17], v[16:17], v[26:27]
	s_waitcnt lgkmcnt(7)
	v_mov_b32_e32 v50, v58
	v_mov_b32_e32 v51, v60
	v_mov_b32_e32 v60, v59
	s_waitcnt lgkmcnt(6)
	v_mov_b32_e32 v54, v62
	v_mov_b32_e32 v55, v64
	v_mov_b32_e32 v64, v63
	s_waitcnt lgkmcnt(5)
	v_mov_b32_e32 v58, v66
	v_mov_b32_e32 v59, v68
	v_mov_b32_e32 v68, v67
	s_waitcnt lgkmcnt(4)
	v_mov_b32_e32 v62, v70
	v_mov_b32_e32 v63, v72
	v_mov_b32_e32 v72, v71
	v_pk_fma_f32 v[14:15], v[30:31], v[14:15], v[36:37]
	v_pk_mul_f32 v[8:9], v[8:9], v[30:31]
	v_pk_fma_f32 v[10:11], v[34:35], v[10:11], v[48:49]
	v_pk_mul_f32 v[4:5], v[4:5], v[34:35]
	v_pk_fma_f32 v[6:7], v[42:43], v[6:7], v[52:53]
	v_pk_mul_f32 v[0:1], v[0:1], v[42:43]
	v_pk_fma_f32 v[2:3], v[46:47], v[2:3], v[56:57]
	v_pk_mul_f32 v[16:17], v[16:17], v[46:47]
	s_addk_i32 s18, 0x2000
	s_waitcnt lgkmcnt(3)
	v_mov_b32_e32 v66, v74
	v_mov_b32_e32 v67, v76
	v_mov_b32_e32 v76, v75
	s_waitcnt lgkmcnt(2)
	v_mov_b32_e32 v70, v78
	v_mov_b32_e32 v71, v80
	v_mov_b32_e32 v80, v79
	s_waitcnt lgkmcnt(1)
	v_mov_b32_e32 v74, v82
	v_mov_b32_e32 v75, v84
	v_mov_b32_e32 v84, v83
	s_waitcnt lgkmcnt(0)
	v_mov_b32_e32 v78, v86
	v_mov_b32_e32 v79, v88
	v_mov_b32_e32 v88, v87
	v_pk_fma_f32 v[14:15], v[50:51], v[14:15], v[60:61]
	v_pk_mul_f32 v[8:9], v[8:9], v[50:51]
	v_pk_fma_f32 v[10:11], v[54:55], v[10:11], v[64:65]
	v_pk_mul_f32 v[4:5], v[4:5], v[54:55]
	v_pk_fma_f32 v[6:7], v[58:59], v[6:7], v[68:69]
	v_pk_mul_f32 v[0:1], v[0:1], v[58:59]
	v_pk_fma_f32 v[2:3], v[62:63], v[2:3], v[72:73]
	v_pk_mul_f32 v[16:17], v[16:17], v[62:63]
	s_cmpk_eq_u32 s18, 0x8000
	v_pk_fma_f32 v[14:15], v[66:67], v[14:15], v[76:77]
	v_pk_mul_f32 v[8:9], v[8:9], v[66:67]
	v_pk_fma_f32 v[10:11], v[70:71], v[10:11], v[80:81]
	v_pk_mul_f32 v[4:5], v[4:5], v[70:71]
	v_pk_fma_f32 v[6:7], v[74:75], v[6:7], v[84:85]
	v_pk_mul_f32 v[0:1], v[0:1], v[74:75]
	v_pk_fma_f32 v[2:3], v[78:79], v[2:3], v[88:89]
	v_pk_mul_f32 v[16:17], v[16:17], v[78:79]
	s_cbranch_scc0 .LBB0_517
	s_lshl_b32 s8, s33, 11
	v_lshl_or_b32 v40, v45, 1, s8
	v_lshl_add_u64 v[18:19], v[40:41], 2, s[14:15]
	v_mov_b32_e32 v12, v8
	v_mov_b32_e32 v13, v14
	v_mov_b32_e32 v14, v9
	global_store_dwordx4 v[18:19], v[12:15], off sc0 sc1
	s_nop 1
	v_lshl_add_u64 v[12:13], v[18:19], 0, 16
	v_mov_b32_e32 v8, v4
	v_mov_b32_e32 v9, v10
	v_mov_b32_e32 v10, v5
	global_store_dwordx4 v[12:13], v[8:11], off sc0 sc1
	s_nop 1
	v_lshl_add_u64 v[8:9], v[18:19], 0, 32
	v_mov_b32_e32 v4, v0
	v_mov_b32_e32 v5, v6
	v_mov_b32_e32 v6, v1
	global_store_dwordx4 v[8:9], v[4:7], off sc0 sc1
	s_nop 1
	v_lshl_add_u64 v[4:5], v[18:19], 0, 48
	v_mov_b32_e32 v0, v16
	v_mov_b32_e32 v1, v2
	v_mov_b32_e32 v2, v17
	global_store_dwordx4 v[4:5], v[0:3], off sc0 sc1
	s_nop 1
	s_mov_b64 s[98:99], exec
	s_mov_b64 exec, 1
	v_mov_b32_e32 v253, 1
	global_atomic_add v253, v41, v253, s[4:5] sc0
	s_mov_b64 exec, s[98:99]
	s_mov_b32 s99, 0
	s_waitcnt vmcnt(0)
